# attention epilogue: 16 row-per-lane dwordx2 stores widened to 8 dwordx4 via v_permlane32_swap (strategy 7.3)
# speedup vs baseline: 1.0020x; 1.0020x over previous
.LBB0_401:
	s_andn2_b64 vcc, exec, s[26:27]
	s_waitcnt lgkmcnt(0)
	s_barrier
	s_cbranch_vccnz .LBB0_403
	v_readlane_b32 s0, v255, 28
	v_readlane_b32 s1, v255, 29
	s_lshl_b64 s[0:1], s[0:1], 2
	v_lshl_add_u32 v0, v0, 2, 0
	v_lshl_add_u64 v[2:3], v[160:161], 0, s[0:1]
	s_lshl_b32 s0, s61, 8
	s_and_b32 s1, s0, 0xc000
	v_add_u32_e32 v82, s1, v0
	ds_read2st64_b32 v[4:5], v82 offset1:1
	ds_read2st64_b32 v[6:7], v82 offset0:2 offset1:3
	ds_read2st64_b32 v[8:9], v82 offset0:4 offset1:5
	ds_read2st64_b32 v[10:11], v82 offset0:6 offset1:7
	ds_read2st64_b32 v[12:13], v82 offset0:8 offset1:9
	ds_read2st64_b32 v[100:101], v82 offset0:10 offset1:11
	ds_read2st64_b32 v[124:125], v82 offset0:12 offset1:13
	ds_read2st64_b32 v[126:127], v82 offset0:14 offset1:15
	s_waitcnt vmcnt(3)
	ds_read2st64_b32 v[128:129], v82 offset0:16 offset1:17
	ds_read2st64_b32 v[130:131], v82 offset0:18 offset1:19
	s_waitcnt vmcnt(2)
	ds_read2st64_b32 v[132:133], v82 offset0:20 offset1:21
	ds_read2st64_b32 v[134:135], v82 offset0:22 offset1:23
	s_waitcnt vmcnt(1)
	ds_read2st64_b32 v[136:137], v82 offset0:24 offset1:25
	ds_read2st64_b32 v[138:139], v82 offset0:26 offset1:27
	s_waitcnt vmcnt(0)
	ds_read2st64_b32 v[140:141], v82 offset0:28 offset1:29
	ds_read2st64_b32 v[142:143], v82 offset0:30 offset1:31
	ds_read2st64_b32 v[144:145], v82 offset0:32 offset1:33
	ds_read2st64_b32 v[146:147], v82 offset0:34 offset1:35
	ds_read2st64_b32 v[122:123], v82 offset0:36 offset1:37
	ds_read2st64_b32 v[152:153], v82 offset0:38 offset1:39
	ds_read2st64_b32 v[116:117], v82 offset0:40 offset1:41
	ds_read2st64_b32 v[120:121], v82 offset0:42 offset1:43
	ds_read2st64_b32 v[110:111], v82 offset0:44 offset1:45
	ds_read2st64_b32 v[114:115], v82 offset0:46 offset1:47
	ds_read2st64_b32 v[106:107], v82 offset0:56 offset1:57
	ds_read2st64_b32 v[108:109], v82 offset0:58 offset1:59
	ds_read2st64_b32 v[14:15], v82 offset0:60 offset1:61
	ds_read_b32 v80, v82 offset:15872
	s_or_b32 s0, s0, 0x3f00
	v_add_u32_e32 v0, s0, v0
	ds_read_b32 v81, v0
	ds_read2st64_b32 v[154:155], v82 offset0:48 offset1:49
	ds_read2st64_b32 v[160:161], v82 offset0:50 offset1:51
	ds_read2st64_b32 v[112:113], v82 offset0:52 offset1:53
	ds_read2st64_b32 v[118:119], v82 offset0:54 offset1:55
	s_waitcnt lgkmcnt(6)
	v_pk_mul_f32 v[14:15], v[156:157], v[14:15]
	s_mulk_i32 s31, 0x880
	v_pk_fma_f32 v[14:15], v[28:29], v[86:87], v[14:15] op_sel_hi:[1,0,1] neg_lo:[0,0,1] neg_hi:[0,0,1]
	s_waitcnt lgkmcnt(4)
	v_pk_mul_f32 v[28:29], v[156:157], v[80:81]
	v_mov_b32_e32 v0, v148
	v_pk_fma_f32 v[84:85], v[30:31], v[86:87], v[28:29] op_sel_hi:[1,0,1] neg_lo:[0,0,1] neg_hi:[0,0,1]
	v_add_u32_e32 v28, s31, v158
	v_ashrrev_i32_e32 v29, 31, v28
	v_readfirstlane_b32 s0, v2
	v_readfirstlane_b32 s1, v3
	v_pk_mul_f32 v[2:3], v[156:157], v[6:7]
	v_lshlrev_b64 v[28:29], 13, v[28:29]
	v_pk_fma_f32 v[92:93], v[66:67], v[86:87], v[2:3] op_sel_hi:[1,0,1] neg_lo:[0,0,1] neg_hi:[0,0,1]
	v_pk_mul_f32 v[2:3], v[156:157], v[4:5]
	v_lshlrev_b32_e32 v0, 2, v0
	v_lshl_add_u64 v[28:29], s[8:9], 0, v[28:29]
	s_lshl_b32 s14, s60, 1
	v_pk_fma_f32 v[98:99], v[64:65], v[86:87], v[2:3] op_sel_hi:[1,0,1] neg_lo:[0,0,1] neg_hi:[0,0,1]
	v_bitop3_b32 v149, v0, s70, v232 bitop3:0x6c
	v_lshl_add_u64 v[28:29], v[28:29], 0, s[14:15]
	v_pk_mul_f32 v[164:165], v[98:99], v[98:99]
	v_lshlrev_b32_e32 v0, 1, v178
	v_pk_mul_f32 v[2:3], v[156:157], v[10:11]
	v_lshlrev_b32_e32 v158, 2, v178
	v_pk_mul_f32 v[162:163], v[92:93], v[92:93]
	v_lshl_add_u64 v[94:95], v[28:29], 0, v[0:1]
	v_pk_fma_f32 v[96:97], v[70:71], v[86:87], v[2:3] op_sel_hi:[1,0,1] neg_lo:[0,0,1] neg_hi:[0,0,1]
	v_pk_mul_f32 v[2:3], v[156:157], v[8:9]
	v_add_f32_e32 v0, v164, v165
	global_load_dwordx4 v[80:83], v158, s[0:1]
	global_load_dwordx4 v[64:67], v158, s[0:1] offset:32
	v_pk_fma_f32 v[102:103], v[68:69], v[86:87], v[2:3] op_sel_hi:[1,0,1] neg_lo:[0,0,1] neg_hi:[0,0,1]
	v_add_f32_e32 v0, v0, v162
	v_pk_mul_f32 v[168:169], v[102:103], v[102:103]
	v_add_f32_e32 v0, v0, v163
	v_pk_mul_f32 v[2:3], v[156:157], v[100:101]
	v_add_f32_e32 v0, v0, v168
	v_pk_mul_f32 v[166:167], v[96:97], v[96:97]
	v_pk_fma_f32 v[100:101], v[74:75], v[86:87], v[2:3] op_sel_hi:[1,0,1] neg_lo:[0,0,1] neg_hi:[0,0,1]
	v_pk_mul_f32 v[2:3], v[156:157], v[12:13]
	v_add_f32_e32 v0, v0, v169
	v_pk_fma_f32 v[104:105], v[72:73], v[86:87], v[2:3] op_sel_hi:[1,0,1] neg_lo:[0,0,1] neg_hi:[0,0,1]
	v_add_f32_e32 v0, v0, v166
	v_pk_mul_f32 v[172:173], v[104:105], v[104:105]
	v_add_f32_e32 v0, v0, v167
	v_pk_mul_f32 v[2:3], v[156:157], v[126:127]
	v_add_f32_e32 v0, v0, v172
	v_pk_mul_f32 v[170:171], v[100:101], v[100:101]
	v_pk_fma_f32 v[78:79], v[78:79], v[86:87], v[2:3] op_sel_hi:[1,0,1] neg_lo:[0,0,1] neg_hi:[0,0,1]
	v_pk_mul_f32 v[2:3], v[156:157], v[124:125]
	v_add_f32_e32 v0, v0, v173
	global_load_dwordx4 v[72:75], v158, s[0:1] offset:64
	global_load_dwordx4 v[68:71], v158, s[0:1] offset:96
	v_pk_fma_f32 v[76:77], v[76:77], v[86:87], v[2:3] op_sel_hi:[1,0,1] neg_lo:[0,0,1] neg_hi:[0,0,1]
	v_add_f32_e32 v0, v0, v170
	v_pk_mul_f32 v[124:125], v[76:77], v[76:77]
	v_add_f32_e32 v0, v0, v171
	v_pk_mul_f32 v[2:3], v[156:157], v[130:131]
	v_add_f32_e32 v0, v0, v124
	v_pk_mul_f32 v[126:127], v[78:79], v[78:79]
	v_pk_fma_f32 v[50:51], v[50:51], v[86:87], v[2:3] op_sel_hi:[1,0,1] neg_lo:[0,0,1] neg_hi:[0,0,1]
	v_pk_mul_f32 v[2:3], v[156:157], v[128:129]
	v_add_f32_e32 v0, v0, v125
	v_pk_fma_f32 v[48:49], v[48:49], v[86:87], v[2:3] op_sel_hi:[1,0,1] neg_lo:[0,0,1] neg_hi:[0,0,1]
	v_add_f32_e32 v0, v0, v126
	v_pk_mul_f32 v[128:129], v[48:49], v[48:49]
	v_add_f32_e32 v0, v0, v127
	v_pk_mul_f32 v[10:11], v[156:157], v[134:135]
	v_add_f32_e32 v0, v0, v128
	v_pk_mul_f32 v[130:131], v[50:51], v[50:51]
	v_pk_fma_f32 v[54:55], v[54:55], v[86:87], v[10:11] op_sel_hi:[1,0,1] neg_lo:[0,0,1] neg_hi:[0,0,1]
	v_pk_mul_f32 v[10:11], v[156:157], v[132:133]
	v_add_f32_e32 v0, v0, v129
	v_pk_fma_f32 v[52:53], v[52:53], v[86:87], v[10:11] op_sel_hi:[1,0,1] neg_lo:[0,0,1] neg_hi:[0,0,1]
	v_add_f32_e32 v0, v0, v130
	v_pk_mul_f32 v[132:133], v[52:53], v[52:53]
	v_add_f32_e32 v0, v0, v131
	v_pk_mul_f32 v[10:11], v[156:157], v[138:139]
	v_add_f32_e32 v0, v0, v132
	v_pk_mul_f32 v[134:135], v[54:55], v[54:55]
	v_pk_fma_f32 v[58:59], v[58:59], v[86:87], v[10:11] op_sel_hi:[1,0,1] neg_lo:[0,0,1] neg_hi:[0,0,1]
	v_pk_mul_f32 v[10:11], v[156:157], v[136:137]
	v_add_f32_e32 v0, v0, v133
	v_pk_fma_f32 v[56:57], v[56:57], v[86:87], v[10:11] op_sel_hi:[1,0,1] neg_lo:[0,0,1] neg_hi:[0,0,1]
	v_add_f32_e32 v0, v0, v134
	v_pk_mul_f32 v[136:137], v[56:57], v[56:57]
	v_add_f32_e32 v0, v0, v135
	v_add_f32_e32 v0, v0, v136
	v_pk_mul_f32 v[138:139], v[58:59], v[58:59]
	v_pk_mul_f32 v[140:141], v[156:157], v[140:141]
	v_add_f32_e32 v0, v0, v137
	v_pk_fma_f32 v[60:61], v[60:61], v[86:87], v[140:141] op_sel_hi:[1,0,1] neg_lo:[0,0,1] neg_hi:[0,0,1]
	v_add_f32_e32 v0, v0, v138
	v_pk_mul_f32 v[142:143], v[156:157], v[142:143]
	v_pk_mul_f32 v[140:141], v[60:61], v[60:61]
	v_add_f32_e32 v0, v0, v139
	v_pk_fma_f32 v[62:63], v[62:63], v[86:87], v[142:143] op_sel_hi:[1,0,1] neg_lo:[0,0,1] neg_hi:[0,0,1]
	v_add_f32_e32 v0, v0, v140
	v_pk_mul_f32 v[142:143], v[62:63], v[62:63]
	v_pk_mul_f32 v[144:145], v[156:157], v[144:145]
	v_add_f32_e32 v0, v0, v141
	v_pk_fma_f32 v[32:33], v[32:33], v[86:87], v[144:145] op_sel_hi:[1,0,1] neg_lo:[0,0,1] neg_hi:[0,0,1]
	v_add_f32_e32 v0, v0, v142
	v_pk_mul_f32 v[146:147], v[156:157], v[146:147]
	v_pk_mul_f32 v[144:145], v[32:33], v[32:33]
	v_add_f32_e32 v0, v0, v143
	v_pk_fma_f32 v[34:35], v[34:35], v[86:87], v[146:147] op_sel_hi:[1,0,1] neg_lo:[0,0,1] neg_hi:[0,0,1]
	v_add_f32_e32 v0, v0, v144
	v_pk_mul_f32 v[146:147], v[34:35], v[34:35]
	v_pk_mul_f32 v[122:123], v[156:157], v[122:123]
	v_add_f32_e32 v0, v0, v145
	v_pk_fma_f32 v[36:37], v[36:37], v[86:87], v[122:123] op_sel_hi:[1,0,1] neg_lo:[0,0,1] neg_hi:[0,0,1]
	v_add_f32_e32 v0, v0, v146
	v_pk_mul_f32 v[152:153], v[156:157], v[152:153]
	v_pk_mul_f32 v[122:123], v[36:37], v[36:37]
	v_add_f32_e32 v0, v0, v147
	v_pk_fma_f32 v[38:39], v[38:39], v[86:87], v[152:153] op_sel_hi:[1,0,1] neg_lo:[0,0,1] neg_hi:[0,0,1]
	v_add_f32_e32 v0, v0, v122
	v_pk_mul_f32 v[152:153], v[38:39], v[38:39]
	v_pk_mul_f32 v[116:117], v[156:157], v[116:117]
	v_add_f32_e32 v0, v0, v123
	v_pk_fma_f32 v[40:41], v[40:41], v[86:87], v[116:117] op_sel_hi:[1,0,1] neg_lo:[0,0,1] neg_hi:[0,0,1]
	v_add_f32_e32 v0, v0, v152
	v_pk_mul_f32 v[120:121], v[156:157], v[120:121]
	v_pk_mul_f32 v[116:117], v[40:41], v[40:41]
	v_add_f32_e32 v0, v0, v153
	v_pk_fma_f32 v[42:43], v[42:43], v[86:87], v[120:121] op_sel_hi:[1,0,1] neg_lo:[0,0,1] neg_hi:[0,0,1]
	v_add_f32_e32 v0, v0, v116
	v_pk_mul_f32 v[120:121], v[42:43], v[42:43]
	v_pk_mul_f32 v[110:111], v[156:157], v[110:111]
	v_add_f32_e32 v0, v0, v117
	v_pk_fma_f32 v[44:45], v[44:45], v[86:87], v[110:111] op_sel_hi:[1,0,1] neg_lo:[0,0,1] neg_hi:[0,0,1]
	v_add_f32_e32 v0, v0, v120
	v_pk_mul_f32 v[114:115], v[156:157], v[114:115]
	v_pk_mul_f32 v[110:111], v[44:45], v[44:45]
	v_add_f32_e32 v0, v0, v121
	v_pk_fma_f32 v[46:47], v[46:47], v[86:87], v[114:115] op_sel_hi:[1,0,1] neg_lo:[0,0,1] neg_hi:[0,0,1]
	v_add_f32_e32 v0, v0, v110
	v_pk_mul_f32 v[114:115], v[46:47], v[46:47]
	s_waitcnt lgkmcnt(3)
	v_pk_mul_f32 v[154:155], v[156:157], v[154:155]
	v_add_f32_e32 v0, v0, v111
	v_pk_fma_f32 v[16:17], v[16:17], v[86:87], v[154:155] op_sel_hi:[1,0,1] neg_lo:[0,0,1] neg_hi:[0,0,1]
	v_add_f32_e32 v0, v0, v114
	s_waitcnt lgkmcnt(2)
	v_pk_mul_f32 v[160:161], v[156:157], v[160:161]
	v_pk_mul_f32 v[154:155], v[16:17], v[16:17]
	v_add_f32_e32 v0, v0, v115
	v_pk_fma_f32 v[18:19], v[18:19], v[86:87], v[160:161] op_sel_hi:[1,0,1] neg_lo:[0,0,1] neg_hi:[0,0,1]
	v_add_f32_e32 v0, v0, v154
	v_pk_mul_f32 v[160:161], v[18:19], v[18:19]
	s_waitcnt lgkmcnt(1)
	v_pk_mul_f32 v[112:113], v[156:157], v[112:113]
	v_add_f32_e32 v0, v0, v155
	v_pk_fma_f32 v[20:21], v[20:21], v[86:87], v[112:113] op_sel_hi:[1,0,1] neg_lo:[0,0,1] neg_hi:[0,0,1]
	v_add_f32_e32 v0, v0, v160
	s_waitcnt lgkmcnt(0)
	v_pk_mul_f32 v[118:119], v[156:157], v[118:119]
	v_pk_mul_f32 v[112:113], v[20:21], v[20:21]
	v_add_f32_e32 v0, v0, v161
	v_pk_fma_f32 v[22:23], v[22:23], v[86:87], v[118:119] op_sel_hi:[1,0,1] neg_lo:[0,0,1] neg_hi:[0,0,1]
	v_add_f32_e32 v0, v0, v112
	v_pk_mul_f32 v[118:119], v[22:23], v[22:23]
	v_pk_mul_f32 v[106:107], v[156:157], v[106:107]
	v_add_f32_e32 v0, v0, v113
	v_pk_mul_f32 v[108:109], v[156:157], v[108:109]
	v_pk_fma_f32 v[24:25], v[24:25], v[86:87], v[106:107] op_sel_hi:[1,0,1] neg_lo:[0,0,1] neg_hi:[0,0,1]
	v_add_f32_e32 v0, v0, v118
	v_pk_fma_f32 v[26:27], v[26:27], v[86:87], v[108:109] op_sel_hi:[1,0,1] neg_lo:[0,0,1] neg_hi:[0,0,1]
	v_pk_mul_f32 v[86:87], v[24:25], v[24:25]
	v_add_f32_e32 v0, v0, v119
	v_add_f32_e32 v0, v0, v86
	v_pk_mul_f32 v[108:109], v[26:27], v[26:27]
	v_add_f32_e32 v0, v0, v87
	v_add_f32_e32 v0, v0, v108
	v_pk_mul_f32 v[88:89], v[14:15], v[14:15]
	v_add_f32_e32 v0, v0, v109
	v_add_f32_e32 v0, v0, v88
	v_pk_mul_f32 v[90:91], v[84:85], v[84:85]
	global_load_dwordx4 v[6:9], v158, s[0:1] offset:128
	global_load_dwordx4 v[2:5], v158, s[0:1] offset:160
	v_add_f32_e32 v0, v0, v89
	v_add_f32_e32 v0, v0, v90
	v_add_f32_e32 v0, v0, v91
	ds_bpermute_b32 v118, v149, v0
	global_load_dwordx4 v[28:31], v158, s[0:1] offset:192
	global_load_dwordx4 v[10:13], v158, s[0:1] offset:224
	s_mov_b64 s[6:7], 0x2aac0200
	v_lshl_add_u64 v[90:91], v[94:95], 0, s[6:7]
	v_and_b32_e32 v144, 32, v148
	v_lshrrev_b32_e32 v144, 2, v144
	v_mov_b32_e32 v145, 0
	v_lshl_add_u64 v[90:91], v[90:91], 0, v[144:145]
	s_mov_b32 s6, 0x800000
	s_waitcnt lgkmcnt(0)
	v_add_f32_e32 v0, v0, v118
	v_mov_b32_e32 v118, 0x3727c5ac
	v_fmamk_f32 v0, v0, 0x3c000000, v118
	v_mul_f32_e32 v118, 0x4b800000, v0
	v_cmp_gt_f32_e32 vcc, s6, v0
	global_load_dwordx4 v[86:89], v158, s[0:1] offset:256
	global_load_dwordx4 v[106:109], v158, s[0:1] offset:288
	global_load_dwordx4 v[110:113], v158, s[0:1] offset:320
	global_load_dwordx4 v[114:117], v158, s[0:1] offset:352
	v_cndmask_b32_e32 v0, v0, v118, vcc
	v_rsq_f32_e32 v0, v0
	s_mov_b32 s6, 0x2aac0000
	global_load_dwordx4 v[118:121], v158, s[0:1] offset:384
	global_load_dwordx4 v[122:125], v158, s[0:1] offset:416
	global_load_dwordx4 v[126:129], v158, s[0:1] offset:448
	v_mul_f32_e32 v130, 0x45800000, v0
	v_cndmask_b32_e32 v0, v0, v130, vcc
	v_mul_f32_e32 v0, v159, v0
	v_pk_mul_f32 v[98:99], v[98:99], v[0:1] op_sel_hi:[1,0]
	v_pk_mul_f32 v[92:93], v[92:93], v[0:1] op_sel_hi:[1,0]
	s_waitcnt vmcnt(14)
	v_pk_mul_f32 v[80:81], v[80:81], v[98:99]
	v_pk_mul_f32 v[82:83], v[82:83], v[92:93]
	v_cvt_pk_bf16_f32 v132, v80, v81
	v_cvt_pk_bf16_f32 v133, v82, v83
	v_add_co_u32_e32 v82, vcc, s6, v94
	v_pk_mul_f32 v[48:49], v[48:49], v[0:1] op_sel_hi:[1,0]
	s_nop 0
	v_addc_co_u32_e32 v83, vcc, 0, v95, vcc
	v_pk_mul_f32 v[80:81], v[102:103], v[0:1] op_sel_hi:[1,0]
	s_waitcnt vmcnt(10)
	v_pk_mul_f32 v[6:7], v[6:7], v[48:49]
	v_pk_mul_f32 v[64:65], v[64:65], v[80:81]
	v_pk_mul_f32 v[80:81], v[96:97], v[0:1] op_sel_hi:[1,0]
	v_cvt_pk_bf16_f32 v134, v64, v65
	v_pk_mul_f32 v[66:67], v[66:67], v[80:81]
	v_pk_mul_f32 v[48:49], v[50:51], v[0:1] op_sel_hi:[1,0]
	v_cvt_pk_bf16_f32 v135, v66, v67
	s_nop 1
	v_permlane32_swap_b32 v132, v134
	v_permlane32_swap_b32 v133, v135
	global_store_dwordx4 v[90:91], v[132:135], off
	v_pk_mul_f32 v[64:65], v[104:105], v[0:1] op_sel_hi:[1,0]
	v_pk_mul_f32 v[66:67], v[100:101], v[0:1] op_sel_hi:[1,0]
	v_pk_mul_f32 v[64:65], v[72:73], v[64:65]
	v_pk_mul_f32 v[66:67], v[74:75], v[66:67]
	v_cvt_pk_bf16_f32 v136, v64, v65
	v_cvt_pk_bf16_f32 v137, v66, v67
	v_pk_mul_f32 v[64:65], v[76:77], v[0:1] op_sel_hi:[1,0]
	v_pk_mul_f32 v[8:9], v[8:9], v[48:49]
	v_pk_mul_f32 v[64:65], v[68:69], v[64:65]
	v_cvt_pk_bf16_f32 v132, v6, v7
	v_cvt_pk_bf16_f32 v138, v64, v65
	v_pk_mul_f32 v[64:65], v[78:79], v[0:1] op_sel_hi:[1,0]
	v_cvt_pk_bf16_f32 v133, v8, v9
	v_pk_mul_f32 v[64:65], v[70:71], v[64:65]
	v_cvt_pk_bf16_f32 v139, v64, v65
	global_load_dwordx4 v[64:67], v158, s[0:1] offset:480
	v_pk_mul_f32 v[6:7], v[52:53], v[0:1] op_sel_hi:[1,0]
	s_nop 1
	v_permlane32_swap_b32 v136, v138
	v_permlane32_swap_b32 v137, v139
	global_store_dwordx4 v[90:91], v[136:139], off offset:32
	s_waitcnt vmcnt(12)
	v_pk_mul_f32 v[2:3], v[2:3], v[6:7]
	v_pk_mul_f32 v[6:7], v[54:55], v[0:1] op_sel_hi:[1,0]
	v_cvt_pk_bf16_f32 v134, v2, v3
	v_pk_mul_f32 v[4:5], v[4:5], v[6:7]
	s_nop 0
	v_cvt_pk_bf16_f32 v135, v4, v5
	s_nop 1
	v_permlane32_swap_b32 v132, v134
	v_permlane32_swap_b32 v133, v135
	global_store_dwordx4 v[90:91], v[132:135], off offset:64
	v_pk_mul_f32 v[2:3], v[56:57], v[0:1] op_sel_hi:[1,0]
	v_pk_mul_f32 v[4:5], v[58:59], v[0:1] op_sel_hi:[1,0]
	s_waitcnt vmcnt(12)
	v_pk_mul_f32 v[2:3], v[2:3], v[28:29]
	v_pk_mul_f32 v[4:5], v[4:5], v[30:31]
	v_cvt_pk_bf16_f32 v136, v2, v3
	v_cvt_pk_bf16_f32 v137, v4, v5
	v_pk_mul_f32 v[2:3], v[60:61], v[0:1] op_sel_hi:[1,0]
	v_pk_mul_f32 v[4:5], v[62:63], v[0:1] op_sel_hi:[1,0]
	s_waitcnt vmcnt(11)
	v_pk_mul_f32 v[2:3], v[2:3], v[10:11]
	v_pk_mul_f32 v[4:5], v[4:5], v[12:13]
	v_cvt_pk_bf16_f32 v138, v2, v3
	v_cvt_pk_bf16_f32 v139, v4, v5
	s_nop 1
	v_permlane32_swap_b32 v136, v138
	v_permlane32_swap_b32 v137, v139
	global_store_dwordx4 v[90:91], v[136:139], off offset:96
	v_pk_mul_f32 v[2:3], v[32:33], v[0:1] op_sel_hi:[1,0]
	v_pk_mul_f32 v[4:5], v[34:35], v[0:1] op_sel_hi:[1,0]
	s_waitcnt vmcnt(11)
	v_pk_mul_f32 v[2:3], v[2:3], v[86:87]
	v_pk_mul_f32 v[4:5], v[4:5], v[88:89]
	v_cvt_pk_bf16_f32 v132, v2, v3
	v_cvt_pk_bf16_f32 v133, v4, v5
	v_pk_mul_f32 v[2:3], v[36:37], v[0:1] op_sel_hi:[1,0]
	v_pk_mul_f32 v[4:5], v[38:39], v[0:1] op_sel_hi:[1,0]
	s_waitcnt vmcnt(10)
	v_pk_mul_f32 v[2:3], v[2:3], v[106:107]
	v_pk_mul_f32 v[4:5], v[4:5], v[108:109]
	v_cvt_pk_bf16_f32 v134, v2, v3
	v_cvt_pk_bf16_f32 v135, v4, v5
	s_nop 1
	v_permlane32_swap_b32 v132, v134
	v_permlane32_swap_b32 v133, v135
	global_store_dwordx4 v[90:91], v[132:135], off offset:128
	v_pk_mul_f32 v[2:3], v[40:41], v[0:1] op_sel_hi:[1,0]
	v_pk_mul_f32 v[4:5], v[42:43], v[0:1] op_sel_hi:[1,0]
	s_waitcnt vmcnt(10)
	v_pk_mul_f32 v[2:3], v[2:3], v[110:111]
	v_pk_mul_f32 v[4:5], v[4:5], v[112:113]
	v_cvt_pk_bf16_f32 v136, v2, v3
	v_cvt_pk_bf16_f32 v137, v4, v5
	v_pk_mul_f32 v[2:3], v[44:45], v[0:1] op_sel_hi:[1,0]
	v_pk_mul_f32 v[4:5], v[46:47], v[0:1] op_sel_hi:[1,0]
	s_waitcnt vmcnt(9)
	v_pk_mul_f32 v[2:3], v[2:3], v[114:115]
	v_pk_mul_f32 v[4:5], v[4:5], v[116:117]
	v_cvt_pk_bf16_f32 v138, v2, v3
	v_cvt_pk_bf16_f32 v139, v4, v5
	s_nop 1
	v_permlane32_swap_b32 v136, v138
	v_permlane32_swap_b32 v137, v139
	global_store_dwordx4 v[90:91], v[136:139], off offset:160
	v_pk_mul_f32 v[2:3], v[16:17], v[0:1] op_sel_hi:[1,0]
	v_pk_mul_f32 v[4:5], v[18:19], v[0:1] op_sel_hi:[1,0]
	s_waitcnt vmcnt(9)
	v_pk_mul_f32 v[2:3], v[2:3], v[118:119]
	v_pk_mul_f32 v[4:5], v[4:5], v[120:121]
	v_cvt_pk_bf16_f32 v132, v2, v3
	v_cvt_pk_bf16_f32 v133, v4, v5
	v_pk_mul_f32 v[2:3], v[20:21], v[0:1] op_sel_hi:[1,0]
	v_pk_mul_f32 v[4:5], v[22:23], v[0:1] op_sel_hi:[1,0]
	s_waitcnt vmcnt(8)
	v_pk_mul_f32 v[2:3], v[2:3], v[122:123]
	v_pk_mul_f32 v[4:5], v[4:5], v[124:125]
	v_cvt_pk_bf16_f32 v134, v2, v3
	v_cvt_pk_bf16_f32 v135, v4, v5
	s_nop 1
	v_permlane32_swap_b32 v132, v134
	v_permlane32_swap_b32 v133, v135
	global_store_dwordx4 v[90:91], v[132:135], off offset:192
	v_pk_mul_f32 v[2:3], v[24:25], v[0:1] op_sel_hi:[1,0]
	v_pk_mul_f32 v[4:5], v[26:27], v[0:1] op_sel_hi:[1,0]
	s_waitcnt vmcnt(8)
	v_pk_mul_f32 v[2:3], v[2:3], v[126:127]
	v_pk_mul_f32 v[4:5], v[4:5], v[128:129]
	v_cvt_pk_bf16_f32 v136, v2, v3
	v_cvt_pk_bf16_f32 v137, v4, v5
	v_pk_mul_f32 v[2:3], v[14:15], v[0:1] op_sel_hi:[1,0]
	v_pk_mul_f32 v[4:5], v[84:85], v[0:1] op_sel_hi:[1,0]
	s_waitcnt vmcnt(6)
	v_pk_mul_f32 v[2:3], v[2:3], v[64:65]
	v_pk_mul_f32 v[4:5], v[4:5], v[66:67]
	v_cvt_pk_bf16_f32 v138, v2, v3
	v_cvt_pk_bf16_f32 v139, v4, v5
	s_nop 1
	v_permlane32_swap_b32 v136, v138
	v_permlane32_swap_b32 v137, v139
	global_store_dwordx4 v[90:91], v[136:139], off offset:224
